# attention softmax rewritten for single-wave ILP: both q-halves interleaved, in-place exp2, 4-way tree row sums
# speedup vs baseline: 1.0119x; 1.0010x over previous
; #define MFMA16(a, b, c) __builtin_amdgcn_mfma_f32_16x16x32_bf16((a), (b), (c), 0, 0, 0)
; DI void u_attn2(Frame& F, int h, int qb, int sp, int ntile) {
;     ...
;             {
;                 bf16x8 kfr[2][4];
; #pragma unroll
;                 for (int kb = 0; kb < 4; ++kb) kfr[0][kb] = ldfrag(Ks, 200, kb * 16, 0, lane);
; #pragma unroll
;                 for (int ks = 0; ks < 6; ++ks) {
;                     if (ks < 5) {
; #pragma unroll
;                         for (int kb = 0; kb < 4; ++kb) kfr[(ks + 1) & 1][kb] = ldfrag(Ks, 200, kb * 16, (ks + 1) * 32, lane); }
; #pragma unroll
;                     for (int kb = 0; kb < 4; ++kb)
; #pragma unroll
;                         for (int qq = 0; qq < 2; ++qq) s[kb][qq] = MFMA16(kfr[ks & 1][kb], qf[qq][ks], s[kb][qq]);
;                 }
;             }
.Latt_A_qk:
	v_cmp_lt_i32_e32 vcc, s46, v179
	s_cbranch_vccz .LBB0_2236
	v_add_u32_e32 v18, s46, v181
	v_cmp_le_i32_e32 vcc, v18, v180
	s_cbranch_vccz .LBB0_2236
	ds_read_b128 v[138:141], v113
	ds_read_b128 v[142:145], v113 offset:6400
	ds_read_b128 v[146:149], v113 offset:12800
	ds_read_b128 v[150:153], v113 offset:19200
	ds_read_b128 v[154:157], v113 offset:64
	ds_read_b128 v[192:195], v113 offset:6464
	ds_read_b128 v[210:213], v113 offset:12864
	ds_read_b128 v[214:217], v113 offset:19264
	s_waitcnt lgkmcnt(7)
	v_mfma_f32_16x16x32_bf16 v[218:221], v[138:141], v[2:5], 0
	ds_read_b128 v[244:247], v113 offset:128
	ds_read_b128 v[248:251], v113 offset:6528
	ds_read_b128 v[198:201], v113 offset:12928
	ds_read_b128 v[230:233], v113 offset:19328
	v_mov_b32_e32 v234, 0x42800000
	v_mfma_f32_16x16x32_bf16 v[138:141], v[138:141], v[30:33], 0
	s_waitcnt lgkmcnt(10)
	v_mfma_f32_16x16x32_bf16 v[222:225], v[142:145], v[2:5], 0
	v_mfma_f32_16x16x32_bf16 v[142:145], v[142:145], v[30:33], 0
	s_waitcnt lgkmcnt(9)
	v_mfma_f32_16x16x32_bf16 v[226:229], v[146:149], v[2:5], 0
	s_waitcnt lgkmcnt(7)
	v_mfma_f32_16x16x32_bf16 v[218:221], v[154:157], v[6:9], v[218:221]
	v_mfma_f32_16x16x32_bf16 v[146:149], v[146:149], v[30:33], 0
	v_mfma_f32_16x16x32_bf16 v[240:243], v[150:153], v[2:5], 0
	v_mfma_f32_16x16x32_bf16 v[150:153], v[150:153], v[30:33], 0
	v_mfma_f32_16x16x32_bf16 v[138:141], v[154:157], v[34:37], v[138:141]
	s_waitcnt lgkmcnt(6)
	v_mfma_f32_16x16x32_bf16 v[154:157], v[192:195], v[6:9], v[222:225]
	v_mfma_f32_16x16x32_bf16 v[142:145], v[192:195], v[34:37], v[142:145]
	s_waitcnt lgkmcnt(5)
	v_mfma_f32_16x16x32_bf16 v[192:195], v[210:213], v[6:9], v[226:229]
	s_waitcnt lgkmcnt(3)
	v_mfma_f32_16x16x32_bf16 v[218:221], v[244:247], v[10:13], v[218:221]
	v_mfma_f32_16x16x32_bf16 v[146:149], v[210:213], v[34:37], v[146:149]
	v_mfma_f32_16x16x32_bf16 v[210:213], v[214:217], v[6:9], v[240:243]
	v_mfma_f32_16x16x32_bf16 v[150:153], v[214:217], v[34:37], v[150:153]
	ds_read_b128 v[214:217], v113 offset:192
	ds_read_b128 v[222:225], v113 offset:6592
	ds_read_b128 v[226:229], v113 offset:12992
	ds_read_b128 v[240:243], v113 offset:19392
	v_mfma_f32_16x16x32_bf16 v[138:141], v[244:247], v[38:41], v[138:141]
	s_waitcnt lgkmcnt(6)
	v_mfma_f32_16x16x32_bf16 v[154:157], v[248:251], v[10:13], v[154:157]
	v_mfma_f32_16x16x32_bf16 v[142:145], v[248:251], v[38:41], v[142:145]
	s_waitcnt lgkmcnt(5)
	v_mfma_f32_16x16x32_bf16 v[192:195], v[198:201], v[10:13], v[192:195]
	s_waitcnt lgkmcnt(3)
	v_mfma_f32_16x16x32_bf16 v[218:221], v[214:217], v[14:17], v[218:221]
	v_mfma_f32_16x16x32_bf16 v[146:149], v[198:201], v[38:41], v[146:149]
	v_mfma_f32_16x16x32_bf16 v[198:201], v[230:233], v[10:13], v[210:213]
	v_mfma_f32_16x16x32_bf16 v[150:153], v[230:233], v[38:41], v[150:153]
	s_nop 1
	ds_read_b128 v[210:213], v113 offset:256
	ds_read_b128 v[230:233], v113 offset:6656
	ds_read_b128 v[244:247], v113 offset:13056
	ds_read_b128 v[248:251], v113 offset:19456
	v_mfma_f32_16x16x32_bf16 v[138:141], v[214:217], v[42:45], v[138:141]
	s_waitcnt lgkmcnt(6)
	v_mfma_f32_16x16x32_bf16 v[154:157], v[222:225], v[14:17], v[154:157]
	v_mfma_f32_16x16x32_bf16 v[142:145], v[222:225], v[42:45], v[142:145]
	s_waitcnt lgkmcnt(5)
	v_mfma_f32_16x16x32_bf16 v[192:195], v[226:229], v[14:17], v[192:195]
	s_waitcnt lgkmcnt(3)
	v_mfma_f32_16x16x32_bf16 v[218:221], v[210:213], v[22:25], v[218:221]
	v_mfma_f32_16x16x32_bf16 v[198:201], v[240:243], v[14:17], v[198:201]
	v_mfma_f32_16x16x32_bf16 v[150:153], v[240:243], v[42:45], v[150:153]
	v_mfma_f32_16x16x32_bf16 v[138:141], v[210:213], v[46:49], v[138:141]
	s_waitcnt lgkmcnt(2)
	v_mfma_f32_16x16x32_bf16 v[154:157], v[230:233], v[22:25], v[154:157]
	v_mfma_f32_16x16x32_bf16 v[146:149], v[226:229], v[42:45], v[146:149]
	ds_read_b128 v[214:217], v113 offset:320
	ds_read_b128 v[222:225], v113 offset:6720
	ds_read_b128 v[226:229], v113 offset:13120
	ds_read_b128 v[240:243], v113 offset:19520
	v_mfma_f32_16x16x32_bf16 v[142:145], v[230:233], v[46:49], v[142:145]
	s_waitcnt lgkmcnt(5)
	v_mfma_f32_16x16x32_bf16 v[192:195], v[244:247], v[22:25], v[192:195]
	s_waitcnt lgkmcnt(3)
	v_mfma_f32_16x16x32_bf16 v[218:221], v[214:217], v[26:29], v[218:221]
	v_mfma_f32_16x16x32_bf16 v[198:201], v[248:251], v[22:25], v[198:201]
	v_mfma_f32_16x16x32_bf16 v[230:233], v[248:251], v[46:49], v[150:153]
	v_mfma_f32_16x16x32_bf16 v[150:153], v[214:217], v[50:53], v[138:141]
	s_waitcnt lgkmcnt(2)
	v_mfma_f32_16x16x32_bf16 v[214:217], v[222:225], v[26:29], v[154:157]
	v_mfma_f32_16x16x32_bf16 v[210:213], v[244:247], v[46:49], v[146:149]
	v_mfma_f32_16x16x32_bf16 v[146:149], v[222:225], v[50:53], v[142:145]
	s_waitcnt lgkmcnt(1)
	v_mfma_f32_16x16x32_bf16 v[222:225], v[226:229], v[26:29], v[192:195]
	s_waitcnt lgkmcnt(0)
; DI float xr16_max(float x) { float a = x, b = x; XR_SWAP("v_permlane16_swap_b32", a, b); return fmaxf(a, b); }
; DI float xr32_max(float x) { float a = x, b = x; XR_SWAP("v_permlane32_swap_b32", a, b); return fmaxf(a, b); }
; DI float xr16_sum(float x) { float a = x, b = x; XR_SWAP("v_permlane16_swap_b32", a, b); return a + b; }
; DI float xr32_sum(float x) { float a = x, b = x; XR_SWAP("v_permlane32_swap_b32", a, b); return a + b; }
; DI void u_attn2(Frame& F, int h, int qb, int sp, int ntile) {
;     ...
;             for (int qq = 0; qq < 2; ++qq) {
;                 float mx = -1e30f;
; #pragma unroll
;                 for (int kb = 0; kb < 4; ++kb) mx = fmaxf(mx, fmaxf(fmaxf(s[kb][qq][0], s[kb][qq][1]), fmaxf(s[kb][qq][2], s[kb][qq][3])));
;                 mx = xr32_max(xr16_max(mx));
;                 const float mn = fmaxf(mrun[qq], mx), alpha = __builtin_amdgcn_exp2f(mrun[qq] - mn); mrun[qq] = mn;
;                 float ps = 0.f; float p[16];
; #pragma unroll
;                 for (int kb = 0; kb < 4; ++kb)
; #pragma unroll
;                     for (int r = 0; r < 4; ++r) { p[kb * 4 + r] = __builtin_amdgcn_exp2f(s[kb][qq][r] - mn); ps += p[kb * 4 + r]; }
;                 ps = xr32_sum(xr16_sum(ps));
;                 lrun[qq] = lrun[qq] * alpha + ps;
; if (__builtin_amdgcn_ballot_w64(alpha != 1.0f) != 0ull) {
; #pragma unroll
;                     for (int db = 0; db < 8; ++db) o[db][qq] = o[db][qq] * alpha; }
	v_mfma_f32_16x16x32_bf16 v[154:157], v[240:243], v[26:29], v[198:201]
	v_mfma_f32_16x16x32_bf16 v[138:141], v[240:243], v[50:53], v[230:233]
	s_nop 1
	v_mfma_f32_16x16x32_bf16 v[142:145], v[226:229], v[50:53], v[210:213]
	s_nop 7
	s_nop 1
	v_max3_f32 v198, v218, v219, v220
	v_max3_f32 v210, v150, v151, v152
	v_max3_f32 v199, v221, v214, v215
	v_max3_f32 v211, v153, v146, v147
	v_max3_f32 v200, v216, v217, v222
	v_max3_f32 v212, v148, v149, v142
	v_max3_f32 v201, v223, v224, v225
	v_max3_f32 v213, v143, v144, v145
	v_max3_f32 v192, v154, v155, v156
	v_max3_f32 v193, v138, v139, v140
	v_max3_f32 v198, v198, v199, v157
	v_max3_f32 v210, v210, v211, v141
	v_max3_f32 v200, v200, v201, v192
	v_max3_f32 v212, v212, v213, v193
	v_max3_f32 v18, v198, v200, s1
	v_max3_f32 v20, v210, v212, s1
	v_mov_b32_e32 v198, v18
	v_mov_b32_e32 v210, v20
	s_nop 0
	v_permlane16_swap_b32 v18, v198
	v_permlane16_swap_b32 v20, v210
	s_nop 0
	v_max_f32_e32 v18, v18, v198
	v_max_f32_e32 v20, v20, v210
	v_mov_b32_e32 v198, v18
	v_mov_b32_e32 v210, v20
	s_nop 0
	v_permlane32_swap_b32 v18, v198
	v_permlane32_swap_b32 v20, v210
	s_nop 0
	v_max3_f32 v21, v164, v18, v198
	v_max3_f32 v191, v162, v20, v210
	v_sub_f32_e32 v18, v164, v21
	v_sub_f32_e32 v20, v162, v191
	v_exp_f32_e32 v18, v18
	v_exp_f32_e32 v20, v20
	v_sub_f32_e32 v218, v218, v21
	v_sub_f32_e32 v219, v219, v21
	v_sub_f32_e32 v220, v220, v21
	v_sub_f32_e32 v221, v221, v21
	v_sub_f32_e32 v214, v214, v21
	v_sub_f32_e32 v215, v215, v21
	v_sub_f32_e32 v216, v216, v21
	v_sub_f32_e32 v217, v217, v21
	v_sub_f32_e32 v222, v222, v21
	v_sub_f32_e32 v223, v223, v21
	v_sub_f32_e32 v224, v224, v21
	v_sub_f32_e32 v225, v225, v21
	v_sub_f32_e32 v154, v154, v21
	v_sub_f32_e32 v155, v155, v21
	v_sub_f32_e32 v156, v156, v21
	v_sub_f32_e32 v157, v157, v21
	v_sub_f32_e32 v150, v150, v191
	v_sub_f32_e32 v151, v151, v191
	v_sub_f32_e32 v152, v152, v191
	v_sub_f32_e32 v153, v153, v191
	v_sub_f32_e32 v146, v146, v191
	v_sub_f32_e32 v147, v147, v191
	v_sub_f32_e32 v148, v148, v191
	v_sub_f32_e32 v149, v149, v191
	v_sub_f32_e32 v142, v142, v191
	v_sub_f32_e32 v143, v143, v191
	v_sub_f32_e32 v144, v144, v191
	v_sub_f32_e32 v145, v145, v191
	v_sub_f32_e32 v138, v138, v191
	v_sub_f32_e32 v139, v139, v191
	v_sub_f32_e32 v140, v140, v191
	v_sub_f32_e32 v141, v141, v191
	v_cmp_neq_f32_e32 vcc, 1.0, v18
	s_cbranch_vccz .Latt_r0_A
	v_pk_mul_f32 v[136:137], v[136:137], v[18:19] op_sel_hi:[1,0]
	v_pk_mul_f32 v[134:135], v[134:135], v[18:19] op_sel_hi:[1,0]
	v_pk_mul_f32 v[108:109], v[108:109], v[18:19] op_sel_hi:[1,0]
	v_pk_mul_f32 v[106:107], v[106:107], v[18:19] op_sel_hi:[1,0]
	v_pk_mul_f32 v[100:101], v[100:101], v[18:19] op_sel_hi:[1,0]
	v_pk_mul_f32 v[98:99], v[98:99], v[18:19] op_sel_hi:[1,0]
	v_pk_mul_f32 v[92:93], v[92:93], v[18:19] op_sel_hi:[1,0]
	v_pk_mul_f32 v[90:91], v[90:91], v[18:19] op_sel_hi:[1,0]
	v_pk_mul_f32 v[84:85], v[84:85], v[18:19] op_sel_hi:[1,0]
	v_pk_mul_f32 v[82:83], v[82:83], v[18:19] op_sel_hi:[1,0]
	v_pk_mul_f32 v[72:73], v[72:73], v[18:19] op_sel_hi:[1,0]
	v_pk_mul_f32 v[70:71], v[70:71], v[18:19] op_sel_hi:[1,0]
	v_pk_mul_f32 v[68:69], v[68:69], v[18:19] op_sel_hi:[1,0]
	v_pk_mul_f32 v[66:67], v[66:67], v[18:19] op_sel_hi:[1,0]
	v_pk_mul_f32 v[56:57], v[56:57], v[18:19] op_sel_hi:[1,0]
	v_pk_mul_f32 v[54:55], v[54:55], v[18:19] op_sel_hi:[1,0]
.Latt_r0_A:
	v_cmp_neq_f32_e32 vcc, 1.0, v20
	s_cbranch_vccz .Latt_r1_A
	v_pk_mul_f32 v[120:121], v[120:121], v[20:21] op_sel_hi:[1,0]
	v_pk_mul_f32 v[118:119], v[118:119], v[20:21] op_sel_hi:[1,0]
	v_pk_mul_f32 v[104:105], v[104:105], v[20:21] op_sel_hi:[1,0]
	v_pk_mul_f32 v[102:103], v[102:103], v[20:21] op_sel_hi:[1,0]
	v_pk_mul_f32 v[96:97], v[96:97], v[20:21] op_sel_hi:[1,0]
	v_pk_mul_f32 v[94:95], v[94:95], v[20:21] op_sel_hi:[1,0]
	v_pk_mul_f32 v[88:89], v[88:89], v[20:21] op_sel_hi:[1,0]
	v_pk_mul_f32 v[86:87], v[86:87], v[20:21] op_sel_hi:[1,0]
	v_pk_mul_f32 v[80:81], v[80:81], v[20:21] op_sel_hi:[1,0]
	v_pk_mul_f32 v[78:79], v[78:79], v[20:21] op_sel_hi:[1,0]
	v_pk_mul_f32 v[76:77], v[76:77], v[20:21] op_sel_hi:[1,0]
	v_pk_mul_f32 v[74:75], v[74:75], v[20:21] op_sel_hi:[1,0]
	v_pk_mul_f32 v[60:61], v[60:61], v[20:21] op_sel_hi:[1,0]
	v_pk_mul_f32 v[58:59], v[58:59], v[20:21] op_sel_hi:[1,0]
	v_pk_mul_f32 v[64:65], v[64:65], v[20:21] op_sel_hi:[1,0]
	v_pk_mul_f32 v[62:63], v[62:63], v[20:21] op_sel_hi:[1,0]
; DI unsigned pk2(float lo, float hi) { const f32x2 v = {lo, hi}; const bf16x2_t b = __builtin_convertvector(v, bf16x2_t); return __builtin_bit_cast(unsigned, b); }
; DI float xr16_sum(float x) { float a = x, b = x; XR_SWAP("v_permlane16_swap_b32", a, b); return a + b; }
; DI float xr32_sum(float x) { float a = x, b = x; XR_SWAP("v_permlane32_swap_b32", a, b); return a + b; }
; DI void u_attn2(Frame& F, int h, int qb, int sp, int ntile) {
;     ...
;                 const float mn = fmaxf(mrun[qq], mx), alpha = __builtin_amdgcn_exp2f(mrun[qq] - mn); mrun[qq] = mn;
;                 float ps = 0.f; float p[16];
; #pragma unroll
;                 for (int kb = 0; kb < 4; ++kb)
; #pragma unroll
;                     for (int r = 0; r < 4; ++r) { p[kb * 4 + r] = __builtin_amdgcn_exp2f(s[kb][qq][r] - mn); ps += p[kb * 4 + r]; }
;                 ps = xr32_sum(xr16_sum(ps));
;                 lrun[qq] = lrun[qq] * alpha + ps;
; if (__builtin_amdgcn_ballot_w64(alpha != 1.0f) != 0ull) {
; #pragma unroll
;                     for (int db = 0; db < 8; ++db) o[db][qq] = o[db][qq] * alpha; }
; #pragma unroll
;                 for (int s2 = 0; s2 < 2; ++s2) { u32x4 pw; pw.x = pk2(p[8 * s2], p[8 * s2 + 1]); pw.y = pk2(p[8 * s2 + 2], p[8 * s2 + 3]); pw.z = pk2(p[8 * s2 + 4], p[8 * s2 + 5]); pw.w = pk2(p[8 * s2 + 6], p[8 * s2 + 7]); pf[qq][s2] = __builtin_bit_cast(bf16x8, pw); }
.Latt_r1_A:
	v_exp_f32_e32 v218, v218
	v_exp_f32_e32 v219, v219
	v_exp_f32_e32 v220, v220
	v_exp_f32_e32 v221, v221
	v_exp_f32_e32 v214, v214
	v_exp_f32_e32 v215, v215
	v_exp_f32_e32 v216, v216
	v_exp_f32_e32 v217, v217
	v_exp_f32_e32 v222, v222
	v_exp_f32_e32 v223, v223
	v_exp_f32_e32 v224, v224
	v_exp_f32_e32 v225, v225
	v_exp_f32_e32 v154, v154
	v_exp_f32_e32 v155, v155
	v_exp_f32_e32 v156, v156
	v_exp_f32_e32 v157, v157
	v_exp_f32_e32 v150, v150
	v_exp_f32_e32 v151, v151
	v_exp_f32_e32 v152, v152
	v_exp_f32_e32 v153, v153
	v_exp_f32_e32 v146, v146
	v_exp_f32_e32 v147, v147
	v_exp_f32_e32 v148, v148
	v_exp_f32_e32 v149, v149
	v_exp_f32_e32 v142, v142
	v_exp_f32_e32 v143, v143
	v_exp_f32_e32 v144, v144
	v_exp_f32_e32 v145, v145
	v_exp_f32_e32 v138, v138
	v_exp_f32_e32 v139, v139
	v_exp_f32_e32 v140, v140
	v_exp_f32_e32 v141, v141
	v_add_f32_e32 v198, v218, v219
	v_add_f32_e32 v199, v220, v221
	v_add_f32_e32 v200, v214, v215
	v_add_f32_e32 v201, v216, v217
	v_add_f32_e32 v210, v150, v151
	v_add_f32_e32 v211, v152, v153
	v_add_f32_e32 v212, v146, v147
	v_add_f32_e32 v213, v148, v149
	v_add_f32_e32 v198, v198, v222
	v_add_f32_e32 v199, v199, v223
	v_add_f32_e32 v200, v200, v224
	v_add_f32_e32 v201, v201, v225
	v_add_f32_e32 v210, v210, v142
	v_add_f32_e32 v211, v211, v143
	v_add_f32_e32 v212, v212, v144
	v_add_f32_e32 v213, v213, v145
	v_add_f32_e32 v198, v198, v154
	v_add_f32_e32 v199, v199, v155
	v_add_f32_e32 v200, v200, v156
	v_add_f32_e32 v201, v201, v157
	v_add_f32_e32 v210, v210, v138
	v_add_f32_e32 v211, v211, v139
	v_add_f32_e32 v212, v212, v140
	v_add_f32_e32 v213, v213, v141
	v_add_f32_e32 v198, v198, v199
	v_add_f32_e32 v200, v200, v201
	v_add_f32_e32 v210, v210, v211
	v_add_f32_e32 v212, v212, v213
	v_add_f32_e32 v198, v198, v200
	v_add_f32_e32 v210, v210, v212
	v_mov_b32_e32 v199, v198
	v_mov_b32_e32 v211, v210
	s_nop 0
	v_permlane16_swap_b32 v198, v199
	v_permlane16_swap_b32 v210, v211
	s_nop 0
	v_add_f32_e32 v198, v198, v199
	v_add_f32_e32 v210, v210, v211
	v_mov_b32_e32 v199, v198
	v_mov_b32_e32 v211, v210
	s_nop 0
	v_permlane32_swap_b32 v198, v199
	v_permlane32_swap_b32 v210, v211
	s_nop 0
	v_add_f32_e32 v198, v198, v199
	v_add_f32_e32 v210, v210, v211
	v_fmac_f32_e32 v198, v165, v18
	v_fmac_f32_e32 v210, v163, v20
	v_mov_b32_e32 v164, v21
	v_mov_b32_e32 v162, v191
	v_mov_b32_e32 v165, v198
	v_mov_b32_e32 v163, v210
	v_cvt_pk_bf16_f32 v198, v218, v219
	v_cvt_pk_bf16_f32 v199, v220, v221
	v_cvt_pk_bf16_f32 v200, v214, v215
	v_cvt_pk_bf16_f32 v201, v216, v217
	v_cvt_pk_bf16_f32 v192, v222, v223
	v_cvt_pk_bf16_f32 v193, v224, v225
	v_cvt_pk_bf16_f32 v194, v154, v155
	v_cvt_pk_bf16_f32 v195, v156, v157
	v_cvt_pk_bf16_f32 v210, v150, v151
	v_cvt_pk_bf16_f32 v211, v152, v153
	v_cvt_pk_bf16_f32 v212, v146, v147
	v_cvt_pk_bf16_f32 v213, v148, v149
	v_cvt_pk_bf16_f32 v142, v142, v143
	v_cvt_pk_bf16_f32 v143, v144, v145
	v_cvt_pk_bf16_f32 v144, v138, v139
	v_cvt_pk_bf16_f32 v145, v140, v141
	s_branch .LBB0_2236
.Latt_gB:
	s_cmp_eq_u32 s46, 0
	s_cbranch_scc1 .Latt_B_qk
	v_add3_u32 v18, s46, v181, -1
	v_cmp_le_i32_e32 vcc, v18, v180
	s_cbranch_vccz .Latt_B_qk
	v_max3_f32 v198, v218, v219, v220
	v_max3_f32 v210, v150, v151, v152
	v_max3_f32 v199, v221, v214, v215
	v_max3_f32 v211, v153, v146, v147
	v_max3_f32 v200, v216, v217, v222
	v_max3_f32 v212, v148, v149, v142
	v_max3_f32 v201, v223, v224, v225
	v_max3_f32 v213, v143, v144, v145
	v_max3_f32 v192, v154, v155, v156
	v_max3_f32 v193, v138, v139, v140
	v_max3_f32 v198, v198, v199, v157
	v_max3_f32 v210, v210, v211, v141
	v_max3_f32 v200, v200, v201, v192
	v_max3_f32 v212, v212, v213, v193
	v_max3_f32 v18, v198, v200, s1
	v_max3_f32 v20, v210, v212, s1
	v_mov_b32_e32 v198, v18
	v_mov_b32_e32 v210, v20
	s_nop 0
	v_permlane16_swap_b32 v18, v198
	v_permlane16_swap_b32 v20, v210
	s_nop 0
	v_max_f32_e32 v18, v18, v198
	v_max_f32_e32 v20, v20, v210
	v_mov_b32_e32 v198, v18
	v_mov_b32_e32 v210, v20
	s_nop 0
	v_permlane32_swap_b32 v18, v198
	v_permlane32_swap_b32 v20, v210
	s_nop 0
	v_max3_f32 v21, v164, v18, v198
	v_max3_f32 v191, v162, v20, v210
	v_sub_f32_e32 v18, v164, v21
	v_sub_f32_e32 v20, v162, v191
	v_exp_f32_e32 v18, v18
	v_exp_f32_e32 v20, v20
	v_sub_f32_e32 v218, v218, v21
	v_sub_f32_e32 v219, v219, v21
	v_sub_f32_e32 v220, v220, v21
	v_sub_f32_e32 v221, v221, v21
	v_sub_f32_e32 v214, v214, v21
	v_sub_f32_e32 v215, v215, v21
	v_sub_f32_e32 v216, v216, v21
	v_sub_f32_e32 v217, v217, v21
	v_sub_f32_e32 v222, v222, v21
	v_sub_f32_e32 v223, v223, v21
	v_sub_f32_e32 v224, v224, v21
	v_sub_f32_e32 v225, v225, v21
	v_sub_f32_e32 v154, v154, v21
	v_sub_f32_e32 v155, v155, v21
	v_sub_f32_e32 v156, v156, v21
	v_sub_f32_e32 v157, v157, v21
	v_sub_f32_e32 v150, v150, v191
	v_sub_f32_e32 v151, v151, v191
	v_sub_f32_e32 v152, v152, v191
	v_sub_f32_e32 v153, v153, v191
	v_sub_f32_e32 v146, v146, v191
	v_sub_f32_e32 v147, v147, v191
	v_sub_f32_e32 v148, v148, v191
	v_sub_f32_e32 v149, v149, v191
	v_sub_f32_e32 v142, v142, v191
	v_sub_f32_e32 v143, v143, v191
	v_sub_f32_e32 v144, v144, v191
	v_sub_f32_e32 v145, v145, v191
	v_sub_f32_e32 v138, v138, v191
	v_sub_f32_e32 v139, v139, v191
	v_sub_f32_e32 v140, v140, v191
	v_sub_f32_e32 v141, v141, v191
	v_cmp_neq_f32_e32 vcc, 1.0, v18
	s_cbranch_vccz .Latt_r0_B
	v_pk_mul_f32 v[136:137], v[136:137], v[18:19] op_sel_hi:[1,0]
	v_pk_mul_f32 v[134:135], v[134:135], v[18:19] op_sel_hi:[1,0]
	v_pk_mul_f32 v[108:109], v[108:109], v[18:19] op_sel_hi:[1,0]
	v_pk_mul_f32 v[106:107], v[106:107], v[18:19] op_sel_hi:[1,0]
	v_pk_mul_f32 v[100:101], v[100:101], v[18:19] op_sel_hi:[1,0]
	v_pk_mul_f32 v[98:99], v[98:99], v[18:19] op_sel_hi:[1,0]
	v_pk_mul_f32 v[92:93], v[92:93], v[18:19] op_sel_hi:[1,0]
	v_pk_mul_f32 v[90:91], v[90:91], v[18:19] op_sel_hi:[1,0]
	v_pk_mul_f32 v[84:85], v[84:85], v[18:19] op_sel_hi:[1,0]
	v_pk_mul_f32 v[82:83], v[82:83], v[18:19] op_sel_hi:[1,0]
	v_pk_mul_f32 v[72:73], v[72:73], v[18:19] op_sel_hi:[1,0]
	v_pk_mul_f32 v[70:71], v[70:71], v[18:19] op_sel_hi:[1,0]
	v_pk_mul_f32 v[68:69], v[68:69], v[18:19] op_sel_hi:[1,0]
	v_pk_mul_f32 v[66:67], v[66:67], v[18:19] op_sel_hi:[1,0]
	v_pk_mul_f32 v[56:57], v[56:57], v[18:19] op_sel_hi:[1,0]
	v_pk_mul_f32 v[54:55], v[54:55], v[18:19] op_sel_hi:[1,0]

; DI unsigned pk2(float lo, float hi) { const f32x2 v = {lo, hi}; const bf16x2_t b = __builtin_convertvector(v, bf16x2_t); return __builtin_bit_cast(unsigned, b); }
; DI float xr16_sum(float x) { float a = x, b = x; XR_SWAP("v_permlane16_swap_b32", a, b); return a + b; }
; DI float xr32_sum(float x) { float a = x, b = x; XR_SWAP("v_permlane32_swap_b32", a, b); return a + b; }
; #define MFMA16(a, b, c) __builtin_amdgcn_mfma_f32_16x16x32_bf16((a), (b), (c), 0, 0, 0)
; #define AT_VLD(dst, db_) { _Pragma("unroll") for (int s2 = 0; s2 < 2; ++s2) { const LAS bf16* vp = Vs + ((db_) * 16 + lc) * 72 + 32 * s2 + 4 * g4; \
;                     const u32x2 v0 = *(const LAS u32x2*)vp, v1 = *(const LAS u32x2*)(vp + 16); const u32x4 vw = (u32x4){v0.x, v0.y, v1.x, v1.y}; dst[s2] = __builtin_bit_cast(bf16x8, vw); } }
; DI void u_attn2(Frame& F, int h, int qb, int sp, int ntile) {
;     ...
;                 const float mn = fmaxf(mrun[qq], mx), alpha = __builtin_amdgcn_exp2f(mrun[qq] - mn); mrun[qq] = mn;
;                 float ps = 0.f; float p[16];
; #pragma unroll
;                 for (int kb = 0; kb < 4; ++kb)
; #pragma unroll
;                     for (int r = 0; r < 4; ++r) { p[kb * 4 + r] = __builtin_amdgcn_exp2f(s[kb][qq][r] - mn); ps += p[kb * 4 + r]; }
;                 ps = xr32_sum(xr16_sum(ps));
;                 lrun[qq] = lrun[qq] * alpha + ps;
; if (__builtin_amdgcn_ballot_w64(alpha != 1.0f) != 0ull) {
; #pragma unroll
;                     for (int db = 0; db < 8; ++db) o[db][qq] = o[db][qq] * alpha; }
; #pragma unroll
;                 for (int s2 = 0; s2 < 2; ++s2) { u32x4 pw; pw.x = pk2(p[8 * s2], p[8 * s2 + 1]); pw.y = pk2(p[8 * s2 + 2], p[8 * s2 + 3]); pw.z = pk2(p[8 * s2 + 4], p[8 * s2 + 5]); pw.w = pk2(p[8 * s2 + 6], p[8 * s2 + 7]); pf[qq][s2] = __builtin_bit_cast(bf16x8, pw); }
;             }
;             {
;                 bf16x8 vfr[2][2];
;     ...
;                 AT_VLD(vfr[0], 0)
; #pragma unroll
;                 for (int db = 0; db < 8; ++db) {
;                     if (db < 7) AT_VLD(vfr[(db + 1) & 1], db + 1)
; #pragma unroll
;                     for (int s2 = 0; s2 < 2; ++s2)
; #pragma unroll
;                         for (int qq = 0; qq < 2; ++qq) o[db][qq] = MFMA16(vfr[db & 1][s2], pf[qq][s2], o[db][qq]);
;                 }
.Latt_r1_B:
	v_exp_f32_e32 v218, v218
	v_exp_f32_e32 v219, v219
	v_exp_f32_e32 v220, v220
	v_exp_f32_e32 v221, v221
	v_exp_f32_e32 v214, v214
	v_exp_f32_e32 v215, v215
	v_exp_f32_e32 v216, v216
	v_exp_f32_e32 v217, v217
	v_exp_f32_e32 v222, v222
	v_exp_f32_e32 v223, v223
	v_exp_f32_e32 v224, v224
	v_exp_f32_e32 v225, v225
	v_exp_f32_e32 v154, v154
	v_exp_f32_e32 v155, v155
	v_exp_f32_e32 v156, v156
	v_exp_f32_e32 v157, v157
	v_exp_f32_e32 v150, v150
	v_exp_f32_e32 v151, v151
	v_exp_f32_e32 v152, v152
	v_exp_f32_e32 v153, v153
	v_exp_f32_e32 v146, v146
	v_exp_f32_e32 v147, v147
	v_exp_f32_e32 v148, v148
	v_exp_f32_e32 v149, v149
	v_exp_f32_e32 v142, v142
	v_exp_f32_e32 v143, v143
	v_exp_f32_e32 v144, v144
	v_exp_f32_e32 v145, v145
	v_exp_f32_e32 v138, v138
	v_exp_f32_e32 v139, v139
	v_exp_f32_e32 v140, v140
	v_exp_f32_e32 v141, v141
	v_add_f32_e32 v198, v218, v219
	v_add_f32_e32 v199, v220, v221
	v_add_f32_e32 v200, v214, v215
	v_add_f32_e32 v201, v216, v217
	v_add_f32_e32 v210, v150, v151
	v_add_f32_e32 v211, v152, v153
	v_add_f32_e32 v212, v146, v147
	v_add_f32_e32 v213, v148, v149
	v_add_f32_e32 v198, v198, v222
	v_add_f32_e32 v199, v199, v223
	v_add_f32_e32 v200, v200, v224
	v_add_f32_e32 v201, v201, v225
	v_add_f32_e32 v210, v210, v142
	v_add_f32_e32 v211, v211, v143
	v_add_f32_e32 v212, v212, v144
	v_add_f32_e32 v213, v213, v145
	v_add_f32_e32 v198, v198, v154
	v_add_f32_e32 v199, v199, v155
	v_add_f32_e32 v200, v200, v156
	v_add_f32_e32 v201, v201, v157
	v_add_f32_e32 v210, v210, v138
	v_add_f32_e32 v211, v211, v139
	v_add_f32_e32 v212, v212, v140
	v_add_f32_e32 v213, v213, v141
	v_add_f32_e32 v198, v198, v199
	v_add_f32_e32 v200, v200, v201
	v_add_f32_e32 v210, v210, v211
	v_add_f32_e32 v212, v212, v213
	v_add_f32_e32 v198, v198, v200
	v_add_f32_e32 v210, v210, v212
	v_mov_b32_e32 v199, v198
	v_mov_b32_e32 v211, v210
	s_nop 0
	v_permlane16_swap_b32 v198, v199
	v_permlane16_swap_b32 v210, v211
	s_nop 0
	v_add_f32_e32 v198, v198, v199
	v_add_f32_e32 v210, v210, v211
	v_mov_b32_e32 v199, v198
	v_mov_b32_e32 v211, v210
	s_nop 0
	v_permlane32_swap_b32 v198, v199
	v_permlane32_swap_b32 v210, v211
	s_nop 0
	v_add_f32_e32 v198, v198, v199
	v_add_f32_e32 v210, v210, v211
	v_fmac_f32_e32 v198, v165, v18
	v_fmac_f32_e32 v210, v163, v20
	v_mov_b32_e32 v164, v21
	v_mov_b32_e32 v162, v191
	v_mov_b32_e32 v165, v198
	v_mov_b32_e32 v163, v210
	v_cvt_pk_bf16_f32 v198, v218, v219
	v_cvt_pk_bf16_f32 v199, v220, v221
	v_cvt_pk_bf16_f32 v200, v214, v215
	v_cvt_pk_bf16_f32 v201, v216, v217
	v_cvt_pk_bf16_f32 v192, v222, v223
	v_cvt_pk_bf16_f32 v193, v224, v225
	v_cvt_pk_bf16_f32 v194, v154, v155
	v_cvt_pk_bf16_f32 v195, v156, v157
	v_cvt_pk_bf16_f32 v210, v150, v151
	v_cvt_pk_bf16_f32 v211, v152, v153
	v_cvt_pk_bf16_f32 v212, v146, v147
	v_cvt_pk_bf16_f32 v213, v148, v149
	v_cvt_pk_bf16_f32 v142, v142, v143
	v_cvt_pk_bf16_f32 v143, v144, v145
	v_cvt_pk_bf16_f32 v144, v138, v139
	v_cvt_pk_bf16_f32 v145, v140, v141
	v_add_u32_e32 v140, 0x6000, v111
	ds_read2_b64 v[146:149], v140 offset0:128 offset1:132
	ds_read2_b64 v[244:247], v140 offset0:136 offset1:140
	v_add_u32_e32 v219, 0x6000, v110
	v_add_u32_e32 v140, 0x6800, v111
	ds_read2_b64 v[220:223], v219 offset0:128 offset1:132
	ds_read2_b64 v[224:227], v219 offset0:136 offset1:140
	s_waitcnt lgkmcnt(3)
	v_mfma_f32_16x16x32_bf16 v[106:109], v[146:149], v[198:201], v[106:109]
	v_mfma_f32_16x16x32_bf16 v[102:105], v[146:149], v[210:213], v[102:105]
	ds_read2_b64 v[146:149], v140 offset0:160 offset1:164
	s_waitcnt lgkmcnt(3)
	v_mfma_f32_16x16x32_bf16 v[106:109], v[244:247], v[192:195], v[106:109]
	v_mfma_f32_16x16x32_bf16 v[102:105], v[244:247], v[142:145], v[102:105]
	ds_read2_b64 v[244:247], v140 offset0:168 offset1:172
	v_add_u32_e32 v140, 0x7000, v111
	s_waitcnt lgkmcnt(1)
	v_mfma_f32_16x16x32_bf16 v[98:101], v[146:149], v[198:201], v[98:101]
	v_mfma_f32_16x16x32_bf16 v[94:97], v[146:149], v[210:213], v[94:97]
	ds_read2_b64 v[146:149], v140 offset0:192 offset1:196
	s_waitcnt lgkmcnt(1)
	v_mfma_f32_16x16x32_bf16 v[98:101], v[244:247], v[192:195], v[98:101]
	v_mfma_f32_16x16x32_bf16 v[94:97], v[244:247], v[142:145], v[94:97]
	ds_read2_b64 v[244:247], v140 offset0:200 offset1:204
	v_add_u32_e32 v140, 0x8800, v112
	s_waitcnt lgkmcnt(1)
	v_mfma_f32_16x16x32_bf16 v[90:93], v[146:149], v[198:201], v[90:93]
	v_mfma_f32_16x16x32_bf16 v[86:89], v[146:149], v[210:213], v[86:89]
	ds_read2_b64 v[146:149], v140 offset1:4
	s_waitcnt lgkmcnt(1)
	v_mfma_f32_16x16x32_bf16 v[90:93], v[244:247], v[192:195], v[90:93]
	v_mfma_f32_16x16x32_bf16 v[86:89], v[244:247], v[142:145], v[86:89]
	ds_read2_b64 v[244:247], v140 offset0:8 offset1:12
	v_add_u32_e32 v140, 0x9000, v112
	s_waitcnt lgkmcnt(1)
	v_mfma_f32_16x16x32_bf16 v[82:85], v[146:149], v[198:201], v[82:85]
	v_mfma_f32_16x16x32_bf16 v[78:81], v[146:149], v[210:213], v[78:81]
	ds_read2_b64 v[146:149], v140 offset0:32 offset1:36
	s_waitcnt lgkmcnt(1)
	v_mfma_f32_16x16x32_bf16 v[82:85], v[244:247], v[192:195], v[82:85]
	v_mfma_f32_16x16x32_bf16 v[78:81], v[244:247], v[142:145], v[78:81]
	ds_read2_b64 v[244:247], v140 offset0:40 offset1:44
	v_add_u32_e32 v140, 0x9800, v112
	s_waitcnt lgkmcnt(1)
	v_mfma_f32_16x16x32_bf16 v[70:73], v[146:149], v[198:201], v[70:73]
	v_mfma_f32_16x16x32_bf16 v[74:77], v[146:149], v[210:213], v[74:77]
	ds_read2_b64 v[146:149], v140 offset0:64 offset1:68
	s_waitcnt lgkmcnt(1)
	v_mfma_f32_16x16x32_bf16 v[70:73], v[244:247], v[192:195], v[70:73]
	v_mfma_f32_16x16x32_bf16 v[74:77], v[244:247], v[142:145], v[74:77]
	ds_read2_b64 v[244:247], v140 offset0:72 offset1:76
	v_add_u32_e32 v140, 0xa000, v112
	s_waitcnt lgkmcnt(1)
	v_mfma_f32_16x16x32_bf16 v[66:69], v[146:149], v[198:201], v[66:69]
	v_mfma_f32_16x16x32_bf16 v[58:61], v[146:149], v[210:213], v[58:61]
	ds_read2_b64 v[146:149], v140 offset0:96 offset1:100
	ds_read2_b64 v[150:153], v140 offset0:104 offset1:108
	s_waitcnt lgkmcnt(2)
	v_mfma_f32_16x16x32_bf16 v[66:69], v[244:247], v[192:195], v[66:69]
	v_mfma_f32_16x16x32_bf16 v[58:61], v[244:247], v[142:145], v[58:61]
	v_mfma_f32_16x16x32_bf16 v[134:137], v[220:223], v[198:201], v[134:137]
	v_mfma_f32_16x16x32_bf16 v[118:121], v[220:223], v[210:213], v[118:121]
	s_waitcnt lgkmcnt(1)
	v_mfma_f32_16x16x32_bf16 v[54:57], v[146:149], v[198:201], v[54:57]
	v_mfma_f32_16x16x32_bf16 v[62:65], v[146:149], v[210:213], v[62:65]
	v_mfma_f32_16x16x32_bf16 v[134:137], v[224:227], v[192:195], v[134:137]
	v_mfma_f32_16x16x32_bf16 v[118:121], v[224:227], v[142:145], v[118:121]
	s_waitcnt lgkmcnt(0)
	v_mfma_f32_16x16x32_bf16 v[54:57], v[150:153], v[192:195], v[54:57]
	v_mfma_f32_16x16x32_bf16 v[62:65], v[150:153], v[142:145], v[62:65]
